# H + indexer scoring loop unrolled by two with key-tile operands prefetched two iterations ahead into separate register sets
# baseline (speedup 1.0000x reference)
; #define LAS __attribute__((address_space(3)))
; __device__ __forceinline__ void idx_scores8(const Params& p, LAS unsigned char* buf, int b, int c, int s8, int pw, int lane, int nw) {
;     ...
;     if (c < 4) return;
;     const int S = 64 * (c + 1); const size_t rowbase = (size_t)b * SEQ; const size_t q0 = rowbase + c * 64 + s8 * 8;
;     const int NVH = (c + 2) >> 1, SP = 64 * NVH;
;     const int r = lane & 31, h = lane >> 5;
;     const int hh = (r >> 2) & 1, reg = (r & 3) + 4 * (r >> 3), ql = (reg >> 3) + 2 * hh, head = reg & 7;
;     bf16x8 af[2][4]; hp2_t wv[2][2][4];
; #pragma unroll
;     for (int rb = 0; rb < 2; ++rb) { const bf16* src = proj + (q0 + rb * 4 + ql) * NPROJ + PC_QI + head * 64 + 32 * h;
; #pragma unroll
;         for (int s = 0; s < 4; ++s) af[rb][s] = *(const bf16x8*)(src + 8 * s);
; #pragma unroll
;         for (int e = 0; e < 2; ++e) { const float* wsrc = wis + (q0 + rb * 4 + 2 * h + e) * 8; const f32x4 w0 = *(const f32x4*)wsrc, w1 = *(const f32x4*)(wsrc + 4);
; #pragma unroll
;             for (int i = 0; i < 2; ++i) { wv[rb][e][i] = (hp2_t){(_Float16)w0[2 * i], (_Float16)w0[2 * i + 1]}; wv[rb][e][2 + i] = (hp2_t){(_Float16)w1[2 * i], (_Float16)w1[2 * i + 1]}; } } }
;     const int nct = S / 32;
;     const bf16* kbase = kir + rowbase * 64 + (4 * h * 32 + r) * 8;
;     LAS unsigned char* rowq = buf + (2 * h) * 8192;
;     bf16x8 bcur[4];
; #pragma unroll
;     for (int s = 0; s < 4; ++s) bcur[s] = *(const bf16x8*)(kbase + (size_t)pw * 2048 + 256 * s);
;     for (int ct = pw; ct < nct; ct += nw) {
;         const int cn = (ct + nw < nct) ? ct + nw : ct;
;         bf16x8 bnx[4];
; #pragma unroll
;         for (int s = 0; s < 4; ++s) bnx[s] = *(const bf16x8*)(kbase + (size_t)cn * 2048 + 256 * s);
.LBB0_3687:
	s_and_b64 vcc, exec, s[0:1]
	s_cbranch_vccz .LBB0_3693
	s_cmp_eq_u32 s84, 16
	s_cbranch_scc1 .LBB0_3693
	s_cmp_lt_u32 s84, 8
	s_cselect_b32 s1, s40, s46
	s_cmp_lt_u32 s1, 4
	s_cbranch_scc1 .LBB0_3693
	s_lshl_b32 s0, s1, 5
	s_add_i32 s4, s0, 64
	s_add_i32 s0, s4, s0
	s_lshr_b32 s0, s0, 5
	v_readlane_b32 s6, v242, 51
	s_cmp_ge_u32 s6, s0
	v_readlane_b32 s7, v242, 52
	s_cbranch_scc1 .LBB0_3693
	s_lshl_b32 s5, s84, 3
	s_lshl_b32 s1, s1, 6
	s_and_b32 s5, s5, 56
	s_or_b32 s1, s1, s5
	v_readlane_b32 s12, v241, 23
	s_or_b32 s6, s12, s1
	v_or_b32_e32 v0, s6, v80
	s_waitcnt vmcnt(0)
	v_mov_b64_e32 v[16:17], s[82:83]
	s_movk_i32 s7, 0x2a00
	v_readlane_b32 s13, v241, 24
	s_and_b32 s1, s4, 0xfc0
	v_mad_u64_u32 v[0:1], s[4:5], v0, s7, v[16:17]
	v_mad_i32_i24 v1, s13, v114, v1
	v_lshl_add_u64 v[0:1], v[0:1], 0, v[78:79]
	v_mov_b32_e32 v89, v79
	v_lshl_add_u64 v[0:1], v[0:1], 0, v[88:89]
	s_mov_b64 s[14:15], 0x2001400
	s_mov_b32 s12, 0x2001000
	v_lshl_add_u64 v[2:3], v[0:1], 0, s[14:15]
	v_add_co_u32_e32 v0, vcc, s12, v0
	v_readlane_b32 s10, v242, 55
	s_nop 0
	v_addc_co_u32_e32 v1, vcc, 0, v1, vcc
	global_load_dwordx4 v[32:35], v[0:1], off offset:1024
	global_load_dwordx4 v[36:39], v[2:3], off offset:16
	global_load_dwordx4 v[40:43], v[2:3], off offset:32
	global_load_dwordx4 v[44:47], v[2:3], off offset:48
	v_mov_b32_e32 v1, s13
	v_or_b32_e32 v0, s6, v82
	v_lshlrev_b64 v[0:1], 5, v[0:1]
	v_readlane_b32 s11, v242, 56
	s_or_b32 s6, s6, 4
	s_nop 0
	v_lshl_add_u64 v[12:13], s[10:11], 0, v[0:1]
	global_load_dwordx4 v[0:3], v[12:13], off offset:48
	global_load_dwordx4 v[4:7], v[12:13], off offset:32
	global_load_dwordx4 v[8:11], v[12:13], off offset:16
	s_nop 0
	global_load_dwordx4 v[12:15], v[12:13], off
	v_or_b32_e32 v160, s6, v80
	v_mad_u64_u32 v[160:161], s[4:5], v160, s7, v[16:17]
	v_mad_i32_i24 v161, s13, v114, v161
	v_lshl_add_u64 v[160:161], v[160:161], 0, v[78:79]
	v_lshl_add_u64 v[160:161], v[160:161], 0, v[88:89]
	v_lshl_add_u64 v[162:163], v[160:161], 0, s[14:15]
	v_add_co_u32_e32 v160, vcc, s12, v160
	s_nop 1
	v_addc_co_u32_e32 v161, vcc, 0, v161, vcc
	global_load_dwordx4 v[48:51], v[160:161], off offset:1024
	global_load_dwordx4 v[52:55], v[162:163], off offset:16
	global_load_dwordx4 v[56:59], v[162:163], off offset:32
	global_load_dwordx4 v[60:63], v[162:163], off offset:48
	v_mov_b32_e32 v161, s13
	v_or_b32_e32 v160, s6, v82
	v_lshlrev_b64 v[160:161], 5, v[160:161]
	v_lshl_add_u64 v[164:165], s[10:11], 0, v[160:161]
	global_load_dwordx4 v[144:147], v[164:165], off offset:48
	global_load_dwordx4 v[148:151], v[164:165], off offset:32
	global_load_dwordx4 v[152:155], v[164:165], off offset:16
	global_load_dwordx4 v[156:159], v[164:165], off
	global_load_dwordx4 v[64:67], v[94:95], off offset:1536
	global_load_dwordx4 v[68:71], v[94:95], off offset:1024
	global_load_dwordx4 v[72:75], v[94:95], off offset:512
	global_load_dwordx4 v[16:19], v[94:95], off
	v_readlane_b32 s6, v242, 51
	v_readlane_b32 s4, v242, 58
	s_mov_b32 s5, s6
	v_readlane_b32 s7, v242, 52
	s_add_i32 s92, s5, 4
	s_cmp_lt_u32 s92, s0
	s_cselect_b32 s92, s92, s5
	s_lshl_b64 s[6:7], s[92:93], 12
	v_lshl_add_u64 v[200:201], v[92:93], 0, s[6:7]
	global_load_dwordx4 v[184:187], v[200:201], off
	global_load_dwordx4 v[188:191], v[200:201], off offset:512
	global_load_dwordx4 v[192:195], v[200:201], off offset:1024
	global_load_dwordx4 v[196:199], v[200:201], off offset:1536
	s_waitcnt vmcnt(16)
	v_cvt_pk_f16_f32 v121, v0, v1
	v_cvt_pk_f16_f32 v123, v2, v3
	v_cvt_pk_f16_f32 v116, v12, v13
	v_cvt_pk_f16_f32 v117, v8, v9
	v_cvt_pk_f16_f32 v118, v14, v15
	v_cvt_pk_f16_f32 v119, v10, v11
	v_cvt_pk_f16_f32 v120, v4, v5
	v_cvt_pk_f16_f32 v122, v6, v7
	s_waitcnt vmcnt(8)
	v_cvt_pk_f16_f32 v128, v144, v145
	v_cvt_pk_f16_f32 v124, v152, v153
	v_cvt_pk_f16_f32 v89, v156, v157
	v_cvt_pk_f16_f32 v125, v158, v159
	v_cvt_pk_f16_f32 v126, v154, v155
	v_cvt_pk_f16_f32 v127, v148, v149
	v_cvt_pk_f16_f32 v129, v150, v151
	v_cvt_pk_f16_f32 v130, v146, v147
	v_cndmask_b32_e64 v0, 0, 1, s[2:3]
	s_nop 0
	v_lshl_add_u32 v131, v0, 16, v112
	s_waitcnt vmcnt(4)
; #define LAS __attribute__((address_space(3)))
; __device__ __forceinline__ void idx_epi(const f32x16& acc, const hp2_t (&wv)[2][4], LAS unsigned char* dst  ) {
;     const hp2_t zero2 = (hp2_t){(_Float16)0.f, (_Float16)0.f};
; #pragma unroll
;     for (int e = 0; e < 2; ++e) { hp2_t sum;
; #pragma unroll
;         for (int i = 0; i < 4; ++i) { hp2_t r = __builtin_bit_cast(hp2_t, __builtin_amdgcn_cvt_pkrtz(acc[8 * e + 2 * i], acc[8 * e + 2 * i + 1])); r = __builtin_elementwise_max(r, zero2);
;             sum = i == 0 ? r * wv[e][0] : __builtin_elementwise_fma(r, wv[e][i], sum); }
;         *(LAS _Float16*)(dst + e * 8192) = sum[0] + sum[1]; }
; __device__ __forceinline__ void idx_scores8(const Params& p, LAS unsigned char* buf, int b, int c, int s8, int pw, int lane, int nw) {
;     ...
;     for (int ct = pw; ct < nct; ct += nw) {
;         const int cn = (ct + nw < nct) ? ct + nw : ct;
;         bf16x8 bnx[4];
; #pragma unroll
;         for (int s = 0; s < 4; ++s) bnx[s] = *(const bf16x8*)(kbase + (size_t)cn * 2048 + 256 * s);
;         const int s0 = ct * 32; const int hf = (s0 >= SP) ? 1 : 0;
;         LAS unsigned char* dst = rowq + (s0 - hf * SP + r) * 4 + 2 * hf;
;         f32x16 accA, accB;
; #pragma unroll
;         for (int i = 0; i < 16; ++i) { accA[i] = 0.f; accB[i] = 0.f; }
; #pragma unroll
;         for (int s = 0; s < 4; ++s) accA = __builtin_amdgcn_mfma_f32_32x32x16_bf16(af[0][s], bcur[s], accA, 0, 0, 0);
; #pragma unroll
;         for (int s = 0; s < 4; ++s) accB = __builtin_amdgcn_mfma_f32_32x32x16_bf16(af[1][s], bcur[s], accB, 0, 0, 0);
;         idx_epi(accA, wv[0], dst);
;         idx_epi(accB, wv[1], dst + 4 * 8192);
; #pragma unroll
;         for (int s = 0; s < 4; ++s) bcur[s] = bnx[s];
;     }
.LBB0_3692:
	v_mfma_f32_32x32x16_bf16 v[0:15], v[48:51], v[16:19], 0
	s_add_i32 s10, s5, 4
	s_add_i32 s92, s5, 8
	s_cmp_lt_u32 s92, s0
	s_cselect_b32 s92, s92, s5
	s_lshl_b64 s[6:7], s[92:93], 12
	v_lshl_add_u64 v[200:201], v[92:93], 0, s[6:7]
	s_cmp_lt_u32 s4, s1
	s_cselect_b32 s6, 0, s1
	v_mfma_f32_32x32x16_bf16 v[16:31], v[32:35], v[16:19], 0
	s_cselect_b32 s7, 0, 2
	s_lshl_b32 s6, s6, 2
	s_addk_i32 s4, 0x80
	s_sub_i32 s6, s7, s6
	s_mov_b32 s5, s10
	s_cmp_ge_u32 s10, s0
	v_add_u32_e32 v140, s6, v131
	global_load_dwordx4 v[168:171], v[200:201], off
	v_mfma_f32_32x32x16_bf16 v[0:15], v[52:55], v[72:75], v[0:15]
	v_add_u32_e32 v131, 0x200, v131
	global_load_dwordx4 v[172:175], v[200:201], off offset:512
	v_mfma_f32_32x32x16_bf16 v[16:31], v[36:39], v[72:75], v[16:31]
	global_load_dwordx4 v[176:179], v[200:201], off offset:1024
	v_mfma_f32_32x32x16_bf16 v[0:15], v[56:59], v[68:71], v[0:15]
	global_load_dwordx4 v[180:183], v[200:201], off offset:1536
	v_mfma_f32_32x32x16_bf16 v[16:31], v[40:43], v[68:71], v[16:31]
	v_mfma_f32_32x32x16_bf16 v[16:31], v[44:47], v[64:67], v[16:31]
	v_mfma_f32_32x32x16_bf16 v[0:15], v[60:63], v[64:67], v[0:15]
	s_nop 10
	v_cvt_pkrtz_f16_f32 v16, v16, v17
	v_cvt_pkrtz_f16_f32 v17, v18, v19
	v_cvt_pkrtz_f16_f32 v19, v22, v23
	v_cvt_pkrtz_f16_f32 v23, v24, v25
	v_cvt_pkrtz_f16_f32 v18, v20, v21
	v_cvt_pkrtz_f16_f32 v22, v26, v27
	v_cvt_pkrtz_f16_f32 v21, v28, v29
	v_cvt_pkrtz_f16_f32 v0, v0, v1
	v_cvt_pkrtz_f16_f32 v1, v2, v3
	v_cvt_pkrtz_f16_f32 v3, v6, v7
	v_cvt_pkrtz_f16_f32 v7, v8, v9
	v_pk_max_f16 v8, v16, 0
	v_cvt_pkrtz_f16_f32 v2, v4, v5
	v_cvt_pkrtz_f16_f32 v4, v14, v15
	v_cvt_pkrtz_f16_f32 v6, v10, v11
	v_pk_max_f16 v9, v17, 0
	v_pk_max_f16 v15, v23, 0
	v_pk_max_f16 v0, v0, 0
	v_pk_max_f16 v7, v7, 0
	v_pk_mul_f16 v8, v116, v8
	v_cvt_pkrtz_f16_f32 v5, v12, v13
	v_pk_max_f16 v10, v18, 0
	v_pk_max_f16 v11, v19, 0
	v_pk_max_f16 v14, v22, 0
	v_pk_max_f16 v1, v1, 0
	v_pk_max_f16 v6, v6, 0
	v_pk_mul_f16 v15, v120, v15
	v_pk_mul_f16 v0, v89, v0
	v_pk_mul_f16 v7, v127, v7
	v_pk_fma_f16 v8, v9, v118, v8
	v_cvt_pkrtz_f16_f32 v20, v30, v31
	v_pk_max_f16 v13, v21, 0
	v_pk_max_f16 v2, v2, 0
	v_pk_max_f16 v5, v5, 0
	v_pk_fma_f16 v9, v14, v122, v15
	v_pk_fma_f16 v0, v1, v125, v0
	v_pk_fma_f16 v1, v6, v129, v7
	v_pk_fma_f16 v6, v10, v117, v8
	v_pk_max_f16 v12, v20, 0
	v_pk_max_f16 v3, v3, 0
	v_pk_max_f16 v4, v4, 0
	v_pk_fma_f16 v7, v13, v121, v9
	v_pk_fma_f16 v0, v2, v124, v0
	v_pk_fma_f16 v1, v5, v128, v1
	v_pk_fma_f16 v2, v11, v119, v6
	v_pk_fma_f16 v5, v12, v123, v7
	v_pk_fma_f16 v0, v3, v126, v0
	v_pk_fma_f16 v1, v4, v130, v1
	v_add_f16_sdwa v2, v2, v2 dst_sel:DWORD dst_unused:UNUSED_PAD src0_sel:DWORD src1_sel:WORD_1
	v_add_f16_sdwa v3, v5, v5 dst_sel:DWORD dst_unused:UNUSED_PAD src0_sel:DWORD src1_sel:WORD_1
	v_add_f16_sdwa v0, v0, v0 dst_sel:DWORD dst_unused:UNUSED_PAD src0_sel:DWORD src1_sel:WORD_1
	v_add_f16_sdwa v1, v1, v1 dst_sel:DWORD dst_unused:UNUSED_PAD src0_sel:DWORD src1_sel:WORD_1
	ds_write_b16 v140, v2
	ds_write_b16 v140, v3 offset:8192
	ds_write_b16 v140, v0 offset:32768
	ds_write_b16 v140, v1 offset:40960
	s_waitcnt vmcnt(4)
	v_mov_b64_e32 v[16:17], v[184:185]
	v_mov_b64_e32 v[18:19], v[186:187]
	v_mov_b64_e32 v[72:73], v[188:189]
	v_mov_b64_e32 v[74:75], v[190:191]
	v_mov_b64_e32 v[68:69], v[192:193]
	v_mov_b64_e32 v[70:71], v[194:195]
	v_mov_b64_e32 v[64:65], v[196:197]
	v_mov_b64_e32 v[66:67], v[198:199]
	s_cbranch_scc1 .LBB0_3693
	v_mfma_f32_32x32x16_bf16 v[0:15], v[48:51], v[16:19], 0
	s_add_i32 s10, s5, 4
	s_add_i32 s92, s5, 8
	s_cmp_lt_u32 s92, s0
	s_cselect_b32 s92, s92, s5
	s_lshl_b64 s[6:7], s[92:93], 12
	v_lshl_add_u64 v[200:201], v[92:93], 0, s[6:7]
	s_cmp_lt_u32 s4, s1
	s_cselect_b32 s6, 0, s1
	v_mfma_f32_32x32x16_bf16 v[16:31], v[32:35], v[16:19], 0
	s_cselect_b32 s7, 0, 2
	s_lshl_b32 s6, s6, 2
	s_addk_i32 s4, 0x80
	s_sub_i32 s6, s7, s6
	s_mov_b32 s5, s10
	s_cmp_ge_u32 s10, s0
	v_add_u32_e32 v140, s6, v131
	global_load_dwordx4 v[184:187], v[200:201], off
	v_mfma_f32_32x32x16_bf16 v[0:15], v[52:55], v[72:75], v[0:15]
	v_add_u32_e32 v131, 0x200, v131
	global_load_dwordx4 v[188:191], v[200:201], off offset:512
	v_mfma_f32_32x32x16_bf16 v[16:31], v[36:39], v[72:75], v[16:31]
	global_load_dwordx4 v[192:195], v[200:201], off offset:1024
	v_mfma_f32_32x32x16_bf16 v[0:15], v[56:59], v[68:71], v[0:15]
	global_load_dwordx4 v[196:199], v[200:201], off offset:1536
	v_mfma_f32_32x32x16_bf16 v[16:31], v[40:43], v[68:71], v[16:31]
	v_mfma_f32_32x32x16_bf16 v[16:31], v[44:47], v[64:67], v[16:31]
	v_mfma_f32_32x32x16_bf16 v[0:15], v[60:63], v[64:67], v[0:15]
	s_nop 10
	v_cvt_pkrtz_f16_f32 v16, v16, v17
	v_cvt_pkrtz_f16_f32 v17, v18, v19
	v_cvt_pkrtz_f16_f32 v19, v22, v23
	v_cvt_pkrtz_f16_f32 v23, v24, v25
	v_cvt_pkrtz_f16_f32 v18, v20, v21
	v_cvt_pkrtz_f16_f32 v22, v26, v27
	v_cvt_pkrtz_f16_f32 v21, v28, v29
	v_cvt_pkrtz_f16_f32 v0, v0, v1
	v_cvt_pkrtz_f16_f32 v1, v2, v3
	v_cvt_pkrtz_f16_f32 v3, v6, v7
	v_cvt_pkrtz_f16_f32 v7, v8, v9
	v_pk_max_f16 v8, v16, 0
	v_cvt_pkrtz_f16_f32 v2, v4, v5
	v_cvt_pkrtz_f16_f32 v4, v14, v15
	v_cvt_pkrtz_f16_f32 v6, v10, v11
	v_pk_max_f16 v9, v17, 0
	v_pk_max_f16 v15, v23, 0
	v_pk_max_f16 v0, v0, 0
	v_pk_max_f16 v7, v7, 0
	v_pk_mul_f16 v8, v116, v8
	v_cvt_pkrtz_f16_f32 v5, v12, v13
	v_pk_max_f16 v10, v18, 0
	v_pk_max_f16 v11, v19, 0
	v_pk_max_f16 v14, v22, 0
	v_pk_max_f16 v1, v1, 0
	v_pk_max_f16 v6, v6, 0
	v_pk_mul_f16 v15, v120, v15
	v_pk_mul_f16 v0, v89, v0
	v_pk_mul_f16 v7, v127, v7
	v_pk_fma_f16 v8, v9, v118, v8
	v_cvt_pkrtz_f16_f32 v20, v30, v31
	v_pk_max_f16 v13, v21, 0
	v_pk_max_f16 v2, v2, 0
	v_pk_max_f16 v5, v5, 0
	v_pk_fma_f16 v9, v14, v122, v15
	v_pk_fma_f16 v0, v1, v125, v0
	v_pk_fma_f16 v1, v6, v129, v7
	v_pk_fma_f16 v6, v10, v117, v8
	v_pk_max_f16 v12, v20, 0
	v_pk_max_f16 v3, v3, 0
	v_pk_max_f16 v4, v4, 0
	v_pk_fma_f16 v7, v13, v121, v9
	v_pk_fma_f16 v0, v2, v124, v0
	v_pk_fma_f16 v1, v5, v128, v1
	v_pk_fma_f16 v2, v11, v119, v6
	v_pk_fma_f16 v5, v12, v123, v7
	v_pk_fma_f16 v0, v3, v126, v0
	v_pk_fma_f16 v1, v4, v130, v1
	v_add_f16_sdwa v2, v2, v2 dst_sel:DWORD dst_unused:UNUSED_PAD src0_sel:DWORD src1_sel:WORD_1
	v_add_f16_sdwa v3, v5, v5 dst_sel:DWORD dst_unused:UNUSED_PAD src0_sel:DWORD src1_sel:WORD_1
	v_add_f16_sdwa v0, v0, v0 dst_sel:DWORD dst_unused:UNUSED_PAD src0_sel:DWORD src1_sel:WORD_1
	v_add_f16_sdwa v1, v1, v1 dst_sel:DWORD dst_unused:UNUSED_PAD src0_sel:DWORD src1_sel:WORD_1
	ds_write_b16 v140, v2
	ds_write_b16 v140, v3 offset:8192
	ds_write_b16 v140, v0 offset:32768
	ds_write_b16 v140, v1 offset:40960
	s_waitcnt vmcnt(4)
	v_mov_b64_e32 v[16:17], v[168:169]
	v_mov_b64_e32 v[18:19], v[170:171]
	v_mov_b64_e32 v[72:73], v[172:173]
	v_mov_b64_e32 v[74:75], v[174:175]
	v_mov_b64_e32 v[68:69], v[176:177]
	v_mov_b64_e32 v[70:71], v[178:179]
	v_mov_b64_e32 v[64:65], v[180:181]
	v_mov_b64_e32 v[66:67], v[182:183]
	s_cbranch_scc0 .LBB0_3692
